# split phase 0->1 barrier: workgroups arrive right after their GEMV units (mods published write-through, flat counter) and wait only at the end of phase 0
# speedup vs baseline: 1.0032x; 1.0032x over previous
.LBB0_60:
	v_readlane_b32 s71, v196, 5
	s_cmpk_gt_i32 s71, 0x300
	s_cbranch_scc1 .LBB0_108
	v_and_b32_e32 v1, 15, v0
	v_cvt_f32_ubyte0_e32 v1, v1
	v_mul_f32_e32 v1, 0xbd800000, v1
	v_mov_b32_e32 v2, 0x461c4000
	v_cmp_eq_f32_e32 vcc, 0, v1
	s_mov_b32 s4, 0x3f2aaaab
	s_movk_i32 s8, 0x204
	v_cndmask_b32_e64 v12, v2, 1.0, vcc
	v_frexp_mant_f32_e32 v2, v12
	v_cmp_gt_f32_e64 s[6:7], s4, v2
	s_mov_b32 s4, 0x3f317218
	s_mov_b32 s5, 0x3fb8aa3b
	v_cndmask_b32_e64 v3, 1.0, 2.0, s[6:7]
	v_mul_f32_e32 v2, v2, v3
	v_add_f32_e32 v5, 1.0, v2
	v_rcp_f32_e32 v10, v5
	v_add_f32_e32 v3, -1.0, v5
	v_sub_f32_e32 v7, v2, v3
	v_add_f32_e32 v3, -1.0, v2
	v_mul_f32_e32 v11, v3, v10
	v_mul_f32_e32 v4, v5, v11
	v_fma_f32 v6, v11, v5, -v4
	v_fmac_f32_e32 v6, v11, v7
	v_add_f32_e32 v2, v4, v6
	v_sub_f32_e32 v5, v3, v2
	v_pk_add_f32 v[8:9], v[2:3], v[4:5] neg_lo:[0,1] neg_hi:[0,1]
	v_mov_b32_e32 v7, v2
	v_pk_add_f32 v[2:3], v[8:9], v[6:7] neg_lo:[0,1] neg_hi:[0,1]
	v_mov_b32_e32 v6, 0x3e91f4c4
	v_add_f32_e32 v2, v2, v3
	v_add_f32_e32 v2, v5, v2
	v_mul_f32_e32 v3, v10, v2
	v_add_f32_e32 v2, v11, v3
	v_sub_f32_e32 v4, v2, v11
	v_sub_f32_e32 v13, v3, v4
	v_mul_f32_e32 v3, v2, v2
	v_fma_f32 v5, v2, v2, -v3
	v_add_f32_e32 v4, v13, v13
	v_fmac_f32_e32 v5, v2, v4
	v_add_f32_e32 v4, v3, v5
	v_fmac_f32_e32 v6, 0x3e76c4e1, v4
	v_fmaak_f32 v6, v4, v6, 0x3ecccdef
	v_sub_f32_e32 v3, v4, v3
	v_sub_f32_e32 v14, v5, v3
	v_mul_f32_e32 v3, v4, v6
	v_fma_f32 v5, v4, v6, -v3
	v_fmac_f32_e32 v5, v14, v6
	v_add_f32_e32 v6, v3, v5
	v_add_f32_e32 v7, 0x3f2aaaaa, v6
	v_sub_f32_e32 v3, v6, v3
	v_sub_f32_e32 v3, v5, v3
	v_add_f32_e32 v5, 0xbf2aaaaa, v7
	v_add_f32_e32 v3, 0x31739010, v3
	v_sub_f32_e32 v5, v6, v5
	v_pk_mul_f32 v[8:9], v[2:3], v[4:5]
	v_pk_add_f32 v[10:11], v[2:3], v[4:5]
	v_fma_f32 v6, v4, v2, -v8
	v_fmac_f32_e32 v6, v4, v13
	v_mov_b32_e32 v9, v11
	v_fmac_f32_e32 v6, v14, v2
	v_pk_add_f32 v[4:5], v[8:9], v[6:7]
	v_ldexp_f32 v14, v13, 1
	v_sub_f32_e32 v3, v4, v8
	v_sub_f32_e32 v3, v6, v3
	v_sub_f32_e32 v6, v7, v5
	v_add_f32_e32 v9, v11, v6
	v_pk_mul_f32 v[6:7], v[4:5], v[4:5] op_sel:[0,1] op_sel_hi:[1,0]
	v_cvt_f64_f32_e32 v[10:11], v12
	v_frexp_exp_i32_f64_e32 v7, v[10:11]
	v_subbrev_co_u32_e64 v7, s[6:7], 0, v7, s[6:7]
	v_cvt_f32_i32_e32 v7, v7
	v_fma_f32 v8, v4, v5, -v6
	v_fmac_f32_e32 v8, v4, v9
	v_fmac_f32_e32 v8, v3, v5
	v_mul_f32_e32 v4, 0x3f317218, v7
	v_fma_f32 v3, v7, s4, -v4
	v_fmamk_f32 v10, v7, 0xb102e308, v3
	v_ldexp_f32 v11, v2, 1
	v_add_f32_e32 v5, v6, v8
	v_pk_add_f32 v[2:3], v[4:5], v[10:11]
	v_mov_b32_e32 v12, v5
	v_mov_b32_e32 v13, v3
	v_mov_b32_e32 v7, v11
	v_pk_add_f32 v[6:7], v[12:13], v[6:7] neg_lo:[0,1] neg_hi:[0,1]
	v_mov_b32_e32 v9, v5
	v_pk_add_f32 v[6:7], v[8:9], v[6:7] neg_lo:[0,1] neg_hi:[0,1]
	v_mov_b32_e32 v11, v2
	v_add_f32_e32 v5, v14, v6
	v_add_f32_e32 v5, v5, v7
	v_pk_add_f32 v[6:7], v[2:3], v[4:5] neg_lo:[0,1] neg_hi:[0,1]
	v_pk_add_f32 v[8:9], v[2:3], v[4:5]
	v_mov_b32_e32 v4, v5
	v_mov_b32_e32 v7, v9
	v_pk_add_f32 v[12:13], v[10:11], v[6:7] neg_lo:[0,1] neg_hi:[0,1]
	v_pk_add_f32 v[6:7], v[10:11], v[6:7]
	v_mov_b32_e32 v5, v2
	v_pk_add_f32 v[10:11], v[6:7], v[2:3] op_sel:[1,0] op_sel_hi:[0,1] neg_lo:[0,1] neg_hi:[0,1]
	v_pk_add_f32 v[14:15], v[8:9], v[10:11] op_sel_hi:[1,0] neg_lo:[0,1] neg_hi:[0,1]
	v_mov_b32_e32 v8, v9
	v_mov_b32_e32 v9, v7
	v_pk_mov_b32 v[10:11], v[2:3], v[10:11] op_sel:[1,0]
	v_mov_b32_e32 v14, v12
	v_pk_add_f32 v[8:9], v[8:9], v[10:11] neg_lo:[0,1] neg_hi:[0,1]
	v_mov_b32_e32 v13, v7
	v_pk_add_f32 v[2:3], v[4:5], v[8:9] neg_lo:[0,1] neg_hi:[0,1]
	s_mov_b32 s4, 0x42b17218
	v_pk_add_f32 v[4:5], v[14:15], v[2:3]
	s_mov_b32 s17, 0x7f800000
	v_pk_add_f32 v[8:9], v[4:5], v[4:5] op_sel:[0,1] op_sel_hi:[1,0]
	v_lshlrev_b32_e32 v62, 2, v0
	v_pk_add_f32 v[6:7], v[6:7], v[8:9] op_sel:[1,0] op_sel_hi:[0,1]
	v_mov_b32_e32 v5, v6
	v_pk_add_f32 v[10:11], v[4:5], v[12:13] neg_lo:[0,1] neg_hi:[0,1]
	v_mov_b32_e32 v3, v8
	v_sub_f32_e32 v4, v4, v10
	v_pk_add_f32 v[2:3], v[2:3], v[10:11] neg_lo:[0,1] neg_hi:[0,1]
	v_sub_f32_e32 v4, v12, v4
	v_add_f32_e32 v2, v2, v4
	v_add_f32_e32 v2, v2, v3
	v_add_f32_e32 v3, v6, v2
	v_sub_f32_e32 v4, v3, v6
	v_sub_f32_e32 v2, v2, v4
	v_mul_f32_e32 v4, v1, v3
	v_fma_f32 v3, v1, v3, -v4
	v_fmac_f32_e32 v3, v1, v2
	v_add_f32_e32 v2, v4, v3
	v_cmp_class_f32_e64 s[6:7], v4, s8
	v_sub_f32_e32 v5, v2, v4
	v_sub_f32_e32 v3, v3, v5
	v_cndmask_b32_e64 v2, v2, v4, s[6:7]
	v_mov_b32_e32 v4, 0x37000000
	v_cmp_eq_f32_e64 s[6:7], s4, v2
	v_mov_b32_e32 v63, 0
	s_mov_b32 s15, 0
	v_cndmask_b32_e64 v4, 0, v4, s[6:7]
	v_sub_f32_e32 v5, v2, v4
	v_mul_f32_e32 v6, 0x3fb8aa3b, v5
	v_fma_f32 v7, v5, s5, -v6
	v_rndne_f32_e32 v8, v6
	v_fmamk_f32 v7, v5, 0x32a5705f, v7
	v_sub_f32_e32 v6, v6, v8
	v_add_f32_e32 v6, v6, v7
	v_exp_f32_e32 v6, v6
	v_cvt_i32_f32_e32 v7, v8
	v_cmp_neq_f32_e64 s[6:7], |v2|, s17
	s_mov_b32 s5, 0xc2ce8ed0
	v_or_b32_e32 v67, 0xfffffe00, v0
	v_cndmask_b32_e64 v2, 0, v3, s[6:7]
	v_ldexp_f32 v3, v6, v7
	v_cmp_ngt_f32_e64 s[6:7], s5, v5
	v_add_f32_e32 v2, v4, v2
	v_mov_b32_e32 v4, 0x7f800000
	v_cndmask_b32_e64 v3, 0, v3, s[6:7]
	v_cmp_nlt_f32_e64 s[6:7], s4, v5
	v_cmp_neq_f32_e64 s[4:5], v1, |v1|
	v_lshrrev_b32_e32 v69, 4, v0
	v_cndmask_b32_e64 v3, v4, v3, s[6:7]
	v_fma_f32 v2, v3, v2, v3
	v_cmp_class_f32_e64 s[6:7], v3, s8
	v_mov_b32_e32 v66, 0xbf1f24be
	s_mov_b32 s16, 0x3e75aa41
	v_cndmask_b32_e64 v2, v2, v3, s[6:7]
	v_cndmask_b32_e64 v3, v4, 0, s[4:5]
	v_cndmask_b32_e64 v3, v3, 1.0, vcc
	v_cmp_class_f32_e64 s[4:5], v1, s8
	s_mov_b32 s18, 0x40490fdb
	v_mov_b32_e32 v68, 0x3e642e9d
	v_cndmask_b32_e64 v1, |v2|, v3, s[4:5]
	v_lshl_add_u64 v[2:3], s[46:47], 0, v[62:63]
	s_mov_b64 s[4:5], 0x1000
	v_lshl_add_u64 v[64:65], v[2:3], 0, s[4:5]
	s_mov_b32 s20, 0x3d4be544
	s_movk_i32 s19, 0x1f8
	s_movk_i32 s21, 0x2000
	s_add_i32 s25, 0, 0x100
	s_mov_b32 s27, 0xfe5163ab
	s_mov_b32 s29, 0x3c439041
	s_mov_b32 s31, 0xdb629599
	s_mov_b32 s35, 0xf534ddc0
	s_mov_b32 s37, 0xfc2757d1
	s_mov_b32 s58, 0x4e441529
	s_mov_b32 s59, 0xa2f9836e
	s_mov_b32 s60, 0x3fc90fda
	s_mov_b32 s61, 0xbfc90fda
	v_mov_b32_e32 v75, 0x3c0881c4
	v_mov_b32_e32 v84, 0xbab64f3b
	s_mov_b64 s[22:23], 0x800
	s_movk_i32 s62, 0x1000
	s_mov_b32 s24, 0x3a000000
	s_mov_b32 s26, 0x40234736
	s_mov_b32 s28, 0xc0a55e0e
	s_mov_b32 s30, 0xbfaad1da
	s_mov_b32 s34, 0x4081e0d3
	s_mov_b32 s36, 0xc09de9e6
	v_mov_b32_e32 v85, 0x1f8
	s_movk_i32 s63, 0x6000
	v_mov_b32_e32 v86, 0x7fc00000
	v_not_b32_e32 v87, 63
	v_not_b32_e32 v88, 31
	v_readlane_b32 s71, v196, 5
	s_mov_b32 s99, 0
	s_branch .LBB0_64

.LBB0_66:
	s_cmp_eq_u32 s99, 1
	s_cbranch_scc1 .Lp0_arr_done_a
	s_mov_b32 s99, 1
	s_waitcnt vmcnt(0)
	s_barrier
	s_mov_b64 s[12:13], exec
	v_readlane_b32 s38, v197, 0
	v_readlane_b32 s39, v197, 1
	s_and_b64 s[38:39], s[12:13], s[38:39]
	s_mov_b64 exec, s[38:39]
	s_cbranch_execz .Lp0_arr_m_a
	v_mov_b32_e32 v251, 0
	v_mov_b32_e32 v252, 1
	global_atomic_add v251, v252, s[92:93] offset:160
.Lp0_arr_m_a:
	s_mov_b64 exec, s[12:13]

.LBB0_108:
	s_cmp_eq_u32 s99, 1
	s_cbranch_scc1 .Lp0_arr_done_b
	s_mov_b32 s99, 1
	s_waitcnt vmcnt(0)
	s_barrier
	s_mov_b64 s[4:5], exec
	v_readlane_b32 s12, v197, 0
	v_readlane_b32 s13, v197, 1
	s_and_b64 s[12:13], s[4:5], s[12:13]
	s_mov_b64 exec, s[12:13]
	s_cbranch_execz .Lp0_arr_m_b
	v_mov_b32_e32 v251, 0
	v_mov_b32_e32 v252, 1
	global_atomic_add v251, v252, s[92:93] offset:160
.Lp0_arr_m_b:
	s_mov_b64 exec, s[4:5]

.LBB0_147:
	s_load_dwordx16 s[4:19], s[0:1], 0x100
	s_cmp_lt_i32 s94, 2
	s_waitcnt lgkmcnt(0)
	v_writelane_b32 v196, s4, 6
	s_nop 1
	v_writelane_b32 v196, s5, 7
	v_writelane_b32 v196, s6, 8
	v_writelane_b32 v196, s7, 9
	v_writelane_b32 v196, s8, 10
	v_writelane_b32 v196, s9, 11
	v_writelane_b32 v196, s10, 12
	v_writelane_b32 v196, s11, 13
	v_writelane_b32 v196, s12, 14
	v_writelane_b32 v196, s13, 15
	v_writelane_b32 v196, s14, 16
	v_writelane_b32 v196, s15, 17
	v_writelane_b32 v196, s16, 18
	v_writelane_b32 v196, s17, 19
	v_writelane_b32 v196, s18, 20
	v_writelane_b32 v196, s19, 21
	s_cselect_b64 s[4:5], -1, 0
	s_cmp_gt_i32 s95, 1
	s_cselect_b64 s[0:1], -1, 0
	s_and_b64 s[0:1], s[4:5], s[0:1]
	s_andn2_b64 vcc, exec, s[0:1]
	s_cbranch_vccnz .LBB0_210
	s_andn2_b64 vcc, exec, s[2:3]
	s_cbranch_vccnz .LBB0_202
	s_waitcnt vmcnt(0) lgkmcnt(0)
	s_barrier
	s_mov_b64 s[0:1], exec
	v_readlane_b32 s2, v197, 0
	v_readlane_b32 s3, v197, 1
	s_and_b64 s[2:3], s[0:1], s[2:3]
	s_mov_b64 exec, s[2:3]
	s_cbranch_execz .Lp0_w_m
	v_mov_b32_e32 v1, 0
.Lp0_spin:
	global_load_dword v2, v1, s[92:93] offset:160 sc1
	s_waitcnt vmcnt(0)
	v_cmp_le_u32_e32 vcc, s66, v2
	s_cbranch_vccnz .Lp0_out
	s_sleep 1
	s_branch .Lp0_spin

.Lp0_w_m:
	s_mov_b64 exec, s[0:1]
	s_barrier
	s_branch .LBB0_202
	s_waitcnt vmcnt(0)
	s_barrier
	s_mov_b64 s[0:1], exec
	v_readlane_b32 s2, v197, 0
	v_readlane_b32 s3, v197, 1
	s_and_b64 s[2:3], s[0:1], s[2:3]
	s_mov_b64 exec, s[2:3]
	s_cbranch_execz .LBB0_201
	s_add_i32 s2, 0, 0x24010
	v_mov_b32_e32 v1, s2
	s_waitcnt vmcnt(0) expcnt(0) lgkmcnt(0)
	ds_read_b32 v3, v1
	s_add_i32 s2, 0, 0x24014
	v_mov_b32_e32 v1, s2
	ds_read_b32 v1, v1
	s_waitcnt lgkmcnt(1)
	v_cmp_ne_u32_e32 vcc, 0, v3
	s_cbranch_vccnz .LBB0_165
	v_readlane_b32 s2, v196, 3
	v_readlane_b32 s3, v196, 4
	s_load_dwordx2 s[8:9], s[2:3], 0x4
	s_add_u32 s2, s92, 0x1000
	s_addc_u32 s3, s93, 0
	s_add_u32 s6, s92, 0x1100
	s_addc_u32 s7, s93, 0
	s_waitcnt lgkmcnt(0)
	s_mul_i32 s18, s8, s66
	s_add_u32 s8, s92, 0x1200
	s_mul_i32 s18, s18, s9
	s_addc_u32 s9, s93, 0
	s_add_u32 s10, s92, 0x1300
	s_addc_u32 s11, s93, 0
	s_mov_b32 s19, 1
	v_mov_b32_e32 v17, 0
	s_branch .LBB0_153
